# same as previous best plus grid-size guard on the XCD-local barrier path
# speedup vs baseline: 1.0239x; 1.0044x over previous
; __device__ __forceinline__ int my_tid(int wave0) { int l; asm volatile("v_mbcnt_lo_u32_b32 %0, -1, 0\n\tv_mbcnt_hi_u32_b32 %0, -1, %0" : "=&v"(l)); return wave0 * 64 + l; }
; __device__ __forceinline__ unsigned xb_add(unsigned* p, unsigned v) { return __hip_atomic_fetch_add(p, v, __ATOMIC_RELAXED, __HIP_MEMORY_SCOPE_AGENT); }
; __device__ __forceinline__ void xcd_barrier(const XcdBarrier& b, bool leader) {
;     asm volatile("s_waitcnt vmcnt(0)" ::: "memory");
;     __syncthreads();
;     if (leader) {
;         unsigned* bar = b.bar;
;         __builtin_amdgcn_s_waitcnt(0);
;         unsigned nloc = b.st[0], nx = b.st[1];
;         if (nloc == 0u) { xcd_barrier_complete(bar, b.x, nloc, nx); b.st[0] = nloc; b.st[1] = nx; }
;         const unsigned old = xb_add(&bar[XB_XSUB(b.x)], 1u);
;         const unsigned gen = old / nloc;
;         if (old + 1u == (gen + 1u) * nloc) {
; __global__ void __launch_bounds__(NWAVES * 64, 2) fwd(Params p) {
;     ...
;         const int L = id / 6, k = id % 6, j = L >> 1; const bool df = (L & 1) != 0;
;         const bool fusedn = (G == 256);
;         if (k == 2 || (k == 0 && L > 0 && fusedn)) continue;
;         if (id > p.ph_lo) xcd_barrier(bar, my_tid(wave0) == 0);
.LBB0_56:
	s_andn2_saveexec_b64 s[6:7], s[6:7]
	s_cbranch_execz .LBB0_76
	s_mov_b64 s[6:7], exec
	v_readlane_b32 s8, v255, 11
	s_cmp_eq_u32 s8, 3
	s_cselect_b32 s9, 1, 0
	s_cmp_eq_u32 s8, 4
	s_cselect_b32 s9, 1, s9
	s_cmp_eq_u32 s9, 0
	s_cbranch_scc1 .Lxb_global
	v_readlane_b32 s9, v253, 0
	s_cmp_eq_u32 s9, 0
	s_cbranch_scc1 .Lxb_global
	v_mov_b32_e32 v8, 0x20808
	ds_read_b32 v9, v8
	s_waitcnt lgkmcnt(0)
	v_readfirstlane_b32 s8, v9
	s_cmp_lg_u32 s8, 0
	s_cbranch_scc1 .Lxb_have
	v_mov_b32_e32 v8, 0x3800
	global_load_dword v9, v8, s[86:87] offset:0 sc1
	global_load_dword v10, v8, s[86:87] offset:256 sc1
	global_load_dword v11, v8, s[86:87] offset:512 sc1
	global_load_dword v12, v8, s[86:87] offset:768 sc1
	global_load_dword v13, v8, s[86:87] offset:1024 sc1
	global_load_dword v14, v8, s[86:87] offset:1280 sc1
	global_load_dword v15, v8, s[86:87] offset:1536 sc1
	global_load_dword v16, v8, s[86:87] offset:1792 sc1
	s_waitcnt vmcnt(0)
	s_mov_b32 s8, 1
	v_readfirstlane_b32 s9, v9
	s_bcnt1_i32_b32 s9, s9
	s_cmp_eq_u32 s9, 1
	s_cselect_b32 s8, s8, 2
	v_readfirstlane_b32 s9, v10
	s_bcnt1_i32_b32 s9, s9
	s_cmp_eq_u32 s9, 1
	s_cselect_b32 s8, s8, 2
	v_readfirstlane_b32 s9, v11
	s_bcnt1_i32_b32 s9, s9
	s_cmp_eq_u32 s9, 1
	s_cselect_b32 s8, s8, 2
	v_readfirstlane_b32 s9, v12
	s_bcnt1_i32_b32 s9, s9
	s_cmp_eq_u32 s9, 1
	s_cselect_b32 s8, s8, 2
	v_readfirstlane_b32 s9, v13
	s_bcnt1_i32_b32 s9, s9
	s_cmp_eq_u32 s9, 1
	s_cselect_b32 s8, s8, 2
	v_readfirstlane_b32 s9, v14
	s_bcnt1_i32_b32 s9, s9
	s_cmp_eq_u32 s9, 1
	s_cselect_b32 s8, s8, 2
	v_readfirstlane_b32 s9, v15
	s_bcnt1_i32_b32 s9, s9
	s_cmp_eq_u32 s9, 1
	s_cselect_b32 s8, s8, 2
	v_readfirstlane_b32 s9, v16
	s_bcnt1_i32_b32 s9, s9
	s_cmp_eq_u32 s9, 1
	s_cselect_b32 s8, s8, 2
	v_mov_b32_e32 v8, 0x20808
	v_mov_b32_e32 v9, s8
	ds_write_b32 v8, v9
	s_waitcnt lgkmcnt(0)
